# v20 + nt (non-temporal) hint on once-read streaming loads: P1 x rows, P7 epilogue x tile, P10 epilogue out tile
# speedup vs baseline: 1.0038x; 1.0038x over previous
; template <bool PARTIALS>
; __device__ __forceinline__ void norm_mod_phase(const float* X, const float* __restrict__ gain, const float* __restrict__ ada_b, const unsigned char* ws, int shift_off, int scale_off, bf16* H, int gw, int NGW, int lane) {
;     ...
;     for (int blk = gw; blk < T / 16; blk += NGW) {
;         const int r0 = blk * 16, b = r0 / SEQ;
;         f32x4 sc[4], sh[4];
; #pragma unroll
;         for (int j = 0; j < 4; ++j) {
;             const int c = 4 * lane + 256 * j;
;             f32x4 s, h;
;             if (PARTIALS) {
;                 s = *(const f32x4*)(ada_b + scale_off + c); h = *(const f32x4*)(ada_b + shift_off + c);
;                 for (int ks = 0; ks < KSPLIT; ++ks) { const float* p = adap + (size_t)(ks * 8 + b) * ADAW; s += *(const f32x4*)(p + scale_off + c); h += *(const f32x4*)(p + shift_off + c); }
;             } else { s = *(const f32x4*)(ada + (size_t)b * ADAW + scale_off + c); h = *(const f32x4*)(ada + (size_t)b * ADAW + shift_off + c); }
;             const f32x4 g = *(const f32x4*)(gain + c);
;             sc[j] = g * (s + 1.0f); sh[j] = h;
;         }
;         f32x4 nv[4];
;         { const f32x4* xr = (const f32x4*)(X + (size_t)r0 * D) + lane;
; #pragma unroll
;           for (int j = 0; j < 4; ++j) nv[j] = xr[64 * j]; }
;         for (int rr = 0; rr < 16; ++rr) {
;             const size_t row = (size_t)(r0 + rr);
;             f32x4 v[4]; float ss = 0.f;
; #pragma unroll
;             for (int j = 0; j < 4; ++j) { v[j] = nv[j]; ss += (v[j].x * v[j].x + v[j].y * v[j].y) + (v[j].z * v[j].z + v[j].w * v[j].w); }
;             { const f32x4* xr = (const f32x4*)(X + (size_t)(r0 + ((rr < 15) ? rr + 1 : 15)) * D) + lane;
; #pragma unroll
;               for (int j = 0; j < 4; ++j) nv[j] = xr[64 * j]; }
.LBB0_138:
	v_lshl_add_u64 v[124:125], v[78:79], 0, s[4:5]
	v_add_co_u32_e32 v80, vcc, 0x2001000, v124
	v_lshl_add_u64 v[128:129], v[76:77], 0, s[4:5]
	s_mov_b64 s[0:1], vcc
	v_add_co_u32_e32 v84, vcc, 0x2000000, v128
	v_addc_co_u32_e64 v81, s[0:1], 0, v125, s[0:1]
	s_mov_b64 s[0:1], vcc
	v_add_co_u32_e32 v88, vcc, 0x2031000, v124
	v_addc_co_u32_e64 v85, s[0:1], 0, v129, s[0:1]
	s_mov_b64 s[0:1], vcc
	v_add_co_u32_e32 v110, vcc, 0x2030000, v128
	v_addc_co_u32_e64 v89, s[0:1], 0, v125, s[0:1]
	s_mov_b64 s[0:1], vcc
	v_add_co_u32_e32 v114, vcc, 0x2061000, v124
	v_addc_co_u32_e64 v111, s[0:1], 0, v129, s[0:1]
	s_mov_b64 s[0:1], vcc
	v_add_co_u32_e32 v118, vcc, 0x2060000, v128
	v_addc_co_u32_e64 v115, s[0:1], 0, v125, s[0:1]
	s_mov_b64 s[0:1], vcc
	global_load_dwordx4 v[80:83], v[80:81], off
	v_add_co_u32_e32 v124, vcc, 0x2091000, v124
	global_load_dwordx4 v[84:87], v[84:85], off offset:3072
	v_addc_co_u32_e64 v119, s[0:1], 0, v129, s[0:1]
	global_load_dwordx4 v[88:91], v[88:89], off
	s_mov_b64 s[0:1], vcc
	global_load_dwordx4 v[110:113], v[110:111], off offset:3072
	v_add_co_u32_e32 v128, vcc, 0x2090000, v128
	global_load_dwordx4 v[114:117], v[114:115], off
	v_addc_co_u32_e64 v125, s[0:1], 0, v125, s[0:1]
	global_load_dwordx4 v[118:121], v[118:119], off offset:3072
	v_addc_co_u32_e32 v129, vcc, 0, v129, vcc
	global_load_dwordx4 v[124:127], v[124:125], off
	s_add_u32 s4, s4, 0xc0000
	global_load_dwordx4 v[128:131], v[128:129], off offset:3072
	s_addc_u32 s5, s5, 0
	s_cmp_lg_u32 s4, 0x300000
	s_waitcnt vmcnt(7)
	v_pk_add_f32 v[82:83], v[94:95], v[82:83]
	v_pk_add_f32 v[80:81], v[92:93], v[80:81]
	s_waitcnt vmcnt(6)
	v_pk_add_f32 v[66:67], v[66:67], v[86:87]
	v_pk_add_f32 v[64:65], v[64:65], v[84:85]
	s_waitcnt vmcnt(5)
	v_pk_add_f32 v[82:83], v[82:83], v[90:91]
	v_pk_add_f32 v[80:81], v[80:81], v[88:89]
	s_waitcnt vmcnt(4)
	v_pk_add_f32 v[66:67], v[66:67], v[112:113]
	v_pk_add_f32 v[64:65], v[64:65], v[110:111]
	s_waitcnt vmcnt(3)
	v_pk_add_f32 v[82:83], v[82:83], v[116:117]
	v_pk_add_f32 v[80:81], v[80:81], v[114:115]
	s_waitcnt vmcnt(2)
	v_pk_add_f32 v[66:67], v[66:67], v[120:121]
	v_pk_add_f32 v[64:65], v[64:65], v[118:119]
	s_waitcnt vmcnt(1)
	v_pk_add_f32 v[94:95], v[82:83], v[126:127]
	v_pk_add_f32 v[92:93], v[80:81], v[124:125]
	s_waitcnt vmcnt(0)
	v_pk_add_f32 v[66:67], v[66:67], v[130:131]
	v_pk_add_f32 v[64:65], v[64:65], v[128:129]
	s_cbranch_scc1 .LBB0_138
	s_lshl_b32 s0, s33, 4
	s_ashr_i32 s1, s0, 31
	s_lshl_b64 s[4:5], s[0:1], 12
	v_lshl_add_u64 v[76:77], v[98:99], 0, s[4:5]
	global_load_dwordx4 v[80:83], v[76:77], off nt
	global_load_dwordx4 v[84:87], v[76:77], off offset:1024 nt
	global_load_dwordx4 v[88:91], v[76:77], off offset:2048 nt
	s_nop 0
	global_load_dwordx4 v[76:79], v[76:77], off offset:3072 nt
	v_pk_add_f32 v[62:63], v[62:63], 1.0 op_sel_hi:[1,0]
	v_pk_add_f32 v[60:61], v[60:61], 1.0 op_sel_hi:[1,0]
	v_pk_mul_f32 v[120:121], v[10:11], v[62:63]
	v_pk_mul_f32 v[118:119], v[8:9], v[60:61]
	v_pk_add_f32 v[60:61], v[74:75], 1.0 op_sel_hi:[1,0]
	v_pk_add_f32 v[62:63], v[72:73], 1.0 op_sel_hi:[1,0]
	v_pk_add_f32 v[70:71], v[70:71], 1.0 op_sel_hi:[1,0]
	v_pk_add_f32 v[68:69], v[68:69], 1.0 op_sel_hi:[1,0]
	v_pk_mul_f32 v[112:113], v[42:43], v[60:61]
	v_pk_mul_f32 v[110:111], v[40:41], v[62:63]
	v_pk_add_f32 v[60:61], v[94:95], 1.0 op_sel_hi:[1,0]
	v_pk_add_f32 v[62:63], v[92:93], 1.0 op_sel_hi:[1,0]
	v_pk_mul_f32 v[116:117], v[14:15], v[70:71]
	v_pk_mul_f32 v[114:115], v[12:13], v[68:69]
	v_pk_mul_f32 v[94:95], v[46:47], v[60:61]
	v_pk_mul_f32 v[92:93], v[44:45], v[62:63]
	s_mov_b32 s1, 0
.LBB0_140:
	s_add_i32 s4, s9, s1
	s_waitcnt vmcnt(2)
	v_pk_mul_f32 v[60:61], v[86:87], v[86:87]
	v_pk_mul_f32 v[62:63], v[84:85], v[84:85]
	v_pk_mul_f32 v[68:69], v[82:83], v[82:83]
	v_pk_mul_f32 v[70:71], v[80:81], v[80:81]
	s_add_i32 s6, s4, 1
	s_waitcnt vmcnt(1)
	v_mul_f32_e32 v72, v88, v88
	v_mul_f32_e32 v74, v90, v90
	v_pk_mov_b32 v[128:129], v[70:71], v[68:69] op_sel:[1,0]
	v_mov_b32_e32 v71, v69
	v_pk_mov_b32 v[68:69], v[62:63], v[60:61] op_sel:[1,0]
	v_mov_b32_e32 v63, v61
	s_ashr_i32 s7, s6, 31
	s_waitcnt vmcnt(0)
	v_mov_b64_e32 v[126:127], v[78:79]
	v_pk_fma_f32 v[130:131], v[88:89], v[88:89], v[72:73] op_sel_hi:[1,1,0]
	v_pk_fma_f32 v[132:133], v[90:91], v[90:91], v[74:75] op_sel_hi:[1,1,0]
	v_pk_add_f32 v[60:61], v[128:129], v[70:71]
	v_pk_add_f32 v[62:63], v[68:69], v[62:63]
	s_lshl_b64 s[6:7], s[6:7], 12
	v_mov_b64_e32 v[124:125], v[76:77]
	v_mul_f32_e32 v130, v76, v76
	v_mul_f32_e32 v132, v77, v77
	v_pk_add_f32 v[128:129], v[60:61], v[60:61] op_sel_hi:[0,1]
	v_pk_add_f32 v[134:135], v[62:63], v[62:63] op_sel_hi:[0,1]
	v_lshl_add_u64 v[76:77], v[98:99], 0, s[6:7]
	v_mul_f32_e32 v128, v78, v78
	v_mul_f32_e32 v134, v79, v79
	global_load_dwordx4 v[72:75], v[76:77], off nt
	global_load_dwordx4 v[68:71], v[76:77], off offset:1024 nt
	global_load_dwordx4 v[60:63], v[76:77], off offset:2048 nt
	s_nop 0
	global_load_dwordx4 v[76:79], v[76:77], off offset:3072 nt
	v_pk_add_f32 v[130:131], v[130:131], v[132:133]
	v_pk_add_f32 v[128:129], v[128:129], v[134:135]
	v_mov_b32_e32 v136, 0
	v_pk_add_f32 v[128:129], v[130:131], v[128:129]
	v_mov_b32_e32 v137, 0
	v_add_f32_e32 v128, v128, v129
	s_ashr_i32 s5, s4, 31
	s_lshl_b64 s[4:5], s[4:5], 11
	v_add_f32_dpp v128, v128, v128 quad_perm:[1,0,3,2] row_mask:0xf bank_mask:0xf bound_ctrl:1
	v_lshl_add_u64 v[132:133], v[100:101], 0, s[4:5]
	s_add_i32 s1, s1, 1
	v_add_f32_dpp v128, v128, v128 quad_perm:[2,3,0,1] row_mask:0xf bank_mask:0xf bound_ctrl:1
	s_cmp_eq_u32 s1, 15
	s_nop 0
	v_add_f32_dpp v128, v128, v128 row_half_mirror row_mask:0xf bank_mask:0xf bound_ctrl:1
	s_nop 1
; __device__ __forceinline__ unsigned pk2(float lo, float hi) { f32x2_t v = {lo, hi}; bf16x2_t b = __builtin_convertvector(v, bf16x2_t); return __builtin_bit_cast(unsigned, b); }
; template <bool PARTIALS>
; __device__ __forceinline__ void norm_mod_phase(const float* X, const float* __restrict__ gain, const float* __restrict__ ada_b, const unsigned char* ws, int shift_off, int scale_off, bf16* H, int gw, int NGW, int lane) {
;     ...
;             const float inv = rsqrtf(wave_sum(ss) * (1.0f / D) + 1e-6f);
;             unsigned long long* o8 = (unsigned long long*)(H + row * D) + lane;
; #pragma unroll
;             for (int j = 0; j < 4; ++j) {
;                 const f32x4 o = v[j] * inv * sc[j] + sh[j];
;                 o8[64 * j] = (unsigned long long)pk2(o.x, o.y) | ((unsigned long long)pk2(o.z, o.w) << 32);
;             }
;         }
	v_add_f32_dpp v128, v128, v128 row_mirror row_mask:0xf bank_mask:0xf bound_ctrl:1
	s_nop 1
	v_mov_b32_dpp v136, v128 row_bcast:15 row_mask:0xa bank_mask:0xf
	v_add_f32_e32 v128, v128, v136
	s_nop 1
	v_mov_b32_dpp v137, v128 row_bcast:31 row_mask:0xc bank_mask:0xf
	v_add_f32_e32 v128, v128, v137
	s_nop 0
	v_readlane_b32 s4, v128, 63
	s_nop 1
	v_fma_f32 v128, s4, v123, v97
	v_mul_f32_e32 v129, 0x4b800000, v128
	v_cmp_gt_f32_e32 vcc, s11, v128
	s_nop 1
	v_cndmask_b32_e32 v128, v128, v129, vcc
	v_rsq_f32_e32 v128, v128
	s_nop 0
	v_mul_f32_e32 v129, 0x45800000, v128
	v_cndmask_b32_e32 v128, v128, v129, vcc
	v_pk_mul_f32 v[80:81], v[80:81], v[128:129] op_sel_hi:[1,0]
	v_pk_mul_f32 v[82:83], v[82:83], v[128:129] op_sel_hi:[1,0]
	v_pk_mul_f32 v[84:85], v[84:85], v[128:129] op_sel_hi:[1,0]
	v_pk_mul_f32 v[86:87], v[86:87], v[128:129] op_sel_hi:[1,0]
	v_pk_mul_f32 v[88:89], v[88:89], v[128:129] op_sel_hi:[1,0]
	v_pk_mul_f32 v[90:91], v[90:91], v[128:129] op_sel_hi:[1,0]
	v_pk_mul_f32 v[124:125], v[124:125], v[128:129] op_sel_hi:[1,0]
	v_pk_mul_f32 v[126:127], v[126:127], v[128:129] op_sel_hi:[1,0]
	v_pk_fma_f32 v[82:83], v[120:121], v[82:83], v[50:51]
	v_pk_fma_f32 v[80:81], v[118:119], v[80:81], v[48:49]
	v_pk_fma_f32 v[86:87], v[116:117], v[86:87], v[54:55]
	v_pk_fma_f32 v[84:85], v[114:115], v[84:85], v[52:53]
	v_pk_fma_f32 v[90:91], v[112:113], v[90:91], v[58:59]
	v_pk_fma_f32 v[88:89], v[110:111], v[88:89], v[56:57]
	v_pk_fma_f32 v[126:127], v[94:95], v[126:127], v[66:67]
	v_pk_fma_f32 v[124:125], v[92:93], v[124:125], v[64:65]
	v_cvt_pk_bf16_f32 v80, v80, v81
	v_cvt_pk_bf16_f32 v81, v82, v83
	v_cvt_pk_bf16_f32 v82, v84, v85
	v_cvt_pk_bf16_f32 v83, v86, v87
	v_cvt_pk_bf16_f32 v84, v88, v89
	v_cvt_pk_bf16_f32 v85, v90, v91
	v_cvt_pk_bf16_f32 v86, v124, v125
	v_cvt_pk_bf16_f32 v87, v126, v127
	global_store_dwordx2 v[132:133], v[80:81], off
	global_store_dwordx2 v[132:133], v[82:83], off offset:512
	global_store_dwordx2 v[132:133], v[84:85], off offset:1024
	global_store_dwordx2 v[132:133], v[86:87], off offset:1536
	s_waitcnt vmcnt(7)
	v_mov_b32_e32 v80, v72
	v_mov_b32_e32 v81, v73
	v_mov_b32_e32 v82, v74
	v_mov_b32_e32 v83, v75
	s_waitcnt vmcnt(6)
	v_mov_b32_e32 v84, v68
	v_mov_b32_e32 v85, v69
	v_mov_b32_e32 v86, v70
	v_mov_b32_e32 v87, v71
	s_waitcnt vmcnt(5)
	v_mov_b32_e32 v88, v60
	v_mov_b32_e32 v89, v61
	v_mov_b32_e32 v90, v62
	v_mov_b32_e32 v91, v63
	s_cbranch_scc0 .LBB0_140
	v_pk_mul_f32 v[80:81], v[74:75], v[74:75]
	v_pk_mul_f32 v[82:83], v[72:73], v[72:73]
	s_or_b32 s0, s0, 15
	v_pk_mov_b32 v[84:85], v[82:83], v[80:81] op_sel:[1,0]
	v_mov_b32_e32 v83, v81
	v_pk_add_f32 v[80:81], v[84:85], v[82:83]
	v_pk_mul_f32 v[82:83], v[70:71], v[70:71]
	v_pk_mul_f32 v[84:85], v[68:69], v[68:69]
	v_pk_add_f32 v[80:81], v[80:81], v[80:81] op_sel:[0,1] op_sel_hi:[1,0]
	v_pk_mov_b32 v[86:87], v[84:85], v[82:83] op_sel:[1,0]
	v_mov_b32_e32 v85, v83
	v_pk_add_f32 v[82:83], v[86:87], v[84:85]
	s_waitcnt vmcnt(4)
	v_mul_f32_e32 v84, v76, v76
	v_mul_f32_e32 v85, v77, v77
	v_pk_add_f32 v[82:83], v[82:83], v[82:83] op_sel:[0,1] op_sel_hi:[1,0]
	v_mov_b32_e32 v81, v84
	v_mov_b32_e32 v83, v85
	v_pk_add_f32 v[80:81], v[80:81], v[82:83]
	v_mul_f32_e32 v82, v61, v61
	v_mul_f32_e32 v84, v63, v63
	v_mul_f32_e32 v86, v78, v78
	v_mul_f32_e32 v87, v79, v79
	v_pk_fma_f32 v[82:83], v[60:61], v[60:61], v[82:83] op_sel_hi:[1,1,0]
	v_pk_fma_f32 v[84:85], v[62:63], v[62:63], v[84:85] op_sel_hi:[1,1,0]
	v_mov_b32_e32 v83, v86
	v_mov_b32_e32 v85, v87
	v_pk_add_f32 v[82:83], v[82:83], v[84:85]
	s_add_i32 s33, s33, s3
	v_pk_add_f32 v[80:81], v[80:81], v[82:83]
	s_add_i32 s9, s9, s10
	v_add_f32_e32 v80, v80, v81
	v_mov_b32_e32 v81, 0
	s_nop 0
	v_add_f32_dpp v80, v80, v80 quad_perm:[1,0,3,2] row_mask:0xf bank_mask:0xf bound_ctrl:1
	s_nop 1
	v_add_f32_dpp v80, v80, v80 quad_perm:[2,3,0,1] row_mask:0xf bank_mask:0xf bound_ctrl:1
	s_nop 1
	v_add_f32_dpp v80, v80, v80 row_half_mirror row_mask:0xf bank_mask:0xf bound_ctrl:1
	s_nop 1
	v_add_f32_dpp v80, v80, v80 row_mirror row_mask:0xf bank_mask:0xf bound_ctrl:1
	s_nop 1
	v_mov_b32_dpp v81, v80 row_bcast:15 row_mask:0xa bank_mask:0xf
	v_add_f32_e32 v80, v80, v81
	v_mov_b32_e32 v81, 0
	s_nop 1
	v_mov_b32_dpp v81, v80 row_bcast:31 row_mask:0xc bank_mask:0xf
	v_add_f32_e32 v80, v80, v81
	s_nop 0
	v_readlane_b32 s1, v80, 63
	s_nop 1
	v_fma_f32 v80, s1, v123, v97
	v_mul_f32_e32 v81, 0x4b800000, v80
	v_cmp_gt_f32_e32 vcc, s11, v80
	s_ashr_i32 s1, s0, 31
	s_lshl_b64 s[0:1], s[0:1], 11
	v_cndmask_b32_e32 v80, v80, v81, vcc
	v_rsq_f32_e32 v80, v80
	v_lshl_add_u64 v[82:83], v[100:101], 0, s[0:1]
	s_cmpk_gt_i32 s33, 0x7ff
	v_mul_f32_e32 v81, 0x45800000, v80
	v_cndmask_b32_e32 v80, v80, v81, vcc
	v_pk_mul_f32 v[72:73], v[72:73], v[80:81] op_sel_hi:[1,0]
	v_pk_mul_f32 v[74:75], v[74:75], v[80:81] op_sel_hi:[1,0]
	v_pk_fma_f32 v[48:49], v[118:119], v[72:73], v[48:49]
	v_pk_fma_f32 v[50:51], v[120:121], v[74:75], v[50:51]
	v_cvt_pk_bf16_f32 v48, v48, v49
	v_cvt_pk_bf16_f32 v49, v50, v51
	global_store_dwordx2 v[82:83], v[48:49], off
	v_pk_mul_f32 v[48:49], v[68:69], v[80:81] op_sel_hi:[1,0]
	v_pk_mul_f32 v[50:51], v[70:71], v[80:81] op_sel_hi:[1,0]
	v_pk_fma_f32 v[48:49], v[114:115], v[48:49], v[52:53]
	v_pk_fma_f32 v[50:51], v[116:117], v[50:51], v[54:55]
	v_cvt_pk_bf16_f32 v48, v48, v49
	v_cvt_pk_bf16_f32 v49, v50, v51
	global_store_dwordx2 v[82:83], v[48:49], off offset:512
	v_pk_mul_f32 v[48:49], v[60:61], v[80:81] op_sel_hi:[1,0]
	v_pk_mul_f32 v[50:51], v[62:63], v[80:81] op_sel_hi:[1,0]
	v_pk_fma_f32 v[48:49], v[110:111], v[48:49], v[56:57]
	v_pk_fma_f32 v[50:51], v[112:113], v[50:51], v[58:59]
	v_cvt_pk_bf16_f32 v48, v48, v49
	v_cvt_pk_bf16_f32 v49, v50, v51
	global_store_dwordx2 v[82:83], v[48:49], off offset:1024
	v_pk_mul_f32 v[48:49], v[76:77], v[80:81] op_sel_hi:[1,0]
	v_pk_mul_f32 v[50:51], v[78:79], v[80:81] op_sel_hi:[1,0]
	v_pk_fma_f32 v[48:49], v[92:93], v[48:49], v[64:65]
	v_pk_fma_f32 v[50:51], v[94:95], v[50:51], v[66:67]
	v_cvt_pk_bf16_f32 v48, v48, v49
	v_cvt_pk_bf16_f32 v49, v50, v51
	global_store_dwordx2 v[82:83], v[48:49], off offset:1536
	s_cbranch_scc0 .LBB0_131

;     __device__ __forceinline__ void operator()(f32x4 (&acc)[2][2][4][2], const Unit& u, int wr, int wc, int fr, int fq) const {
;     ...
;         for (int bj = 0; bj < 2; ++bj) {
;             const int col = col0 + bj * HALF;
;             const f32x4 g0 = *(const f32x4*)(gate + (size_t)b * ADAW + col), g1 = *(const f32x4*)(gate + (size_t)b * ADAW + col + 4);
; #pragma unroll
;             for (int ai = 0; ai < 2; ++ai)
; #pragma unroll
;                 for (int m = 0; m < 4; ++m) {
;                     const size_t off = (size_t)(row0 + ai * HALF + m * 16) * D + col;
;                     const f32x4 x0 = *(const f32x4*)(base + off) + g0 * acc[ai][bj][m][0], x1 = *(const f32x4*)(base + off + 4) + g1 * acc[ai][bj][m][1];
;                     *(f32x4*)(out + off) = x0; *(f32x4*)(out + off + 4) = x1;
.LBB0_740:
	s_ashr_i32 s2, s20, 31
	s_lshr_b32 s2, s2, 28
	s_add_i32 s2, s20, s2
	v_lshl_add_u32 v204, s20, 8, v212
	s_ashr_i32 s3, s2, 4
	v_lshl_add_u32 v202, s0, 8, v214
	s_mul_hi_i32 s2, s3, 0x6000
	s_mulk_i32 s3, 0x6000
	v_ashrrev_i32_e32 v205, 31, v204
	s_add_u32 s22, s54, s3
	v_ashrrev_i32_e32 v203, 31, v202
	v_lshlrev_b64 v[128:129], 10, v[204:205]
	s_addc_u32 s23, s55, s2
	v_lshl_add_u64 v[128:129], v[128:129], 0, v[202:203]
	v_readlane_b32 s72, v242, 18
	v_lshl_add_u64 v[144:145], v[202:203], 2, s[22:23]
	v_lshlrev_b64 v[132:133], 2, v[128:129]
	v_readlane_b32 s73, v242, 19
	global_load_dwordx4 v[136:139], v[144:145], off
	v_or_b32_e32 v198, 16, v204
	v_lshl_add_u64 v[176:177], s[72:73], 0, v[132:133]
	global_load_dwordx4 v[128:131], v[176:177], off nt
	global_load_dwordx4 v[146:149], v[176:177], off offset:16 nt
	global_load_dwordx4 v[140:143], v[144:145], off offset:16
	v_ashrrev_i32_e32 v199, 31, v198
	v_lshlrev_b64 v[134:135], 10, v[198:199]
	v_lshl_add_u64 v[134:135], v[134:135], 0, v[202:203]
	v_lshl_add_u64 v[180:181], s[26:27], 0, v[132:133]
	v_lshlrev_b64 v[150:151], 2, v[134:135]
	v_lshl_add_u64 v[178:179], s[72:73], 0, v[150:151]
	v_or_b32_e32 v194, 32, v204
	v_ashrrev_i32_e32 v195, 31, v194
	v_lshl_add_u64 v[184:185], s[26:27], 0, v[150:151]
	v_or_b32_e32 v190, 48, v204
	v_ashrrev_i32_e32 v191, 31, v190
	v_add_u32_e32 v186, 0x80, v204
	v_ashrrev_i32_e32 v187, 31, v186
	v_add_u32_e32 v174, 0x90, v204
	v_ashrrev_i32_e32 v175, 31, v174
	v_add_u32_e32 v172, 0xa0, v204
	v_ashrrev_i32_e32 v173, 31, v172
	v_add_u32_e32 v170, 0xb0, v204
	v_ashrrev_i32_e32 v171, 31, v170
	s_lshl_b32 s22, s0, 2
	s_ashr_i32 s23, s22, 31
	v_readlane_b32 s74, v242, 20
	v_readlane_b32 s75, v242, 21
	v_readlane_b32 s76, v242, 22
	v_readlane_b32 s77, v242, 23
	v_readlane_b32 s78, v242, 24
	v_readlane_b32 s79, v242, 25
	v_readlane_b32 s80, v242, 26
	v_readlane_b32 s81, v242, 27
	v_readlane_b32 s82, v242, 28
	v_readlane_b32 s83, v242, 29
	v_readlane_b32 s84, v242, 30
	v_readlane_b32 s85, v242, 31
	v_readlane_b32 s86, v242, 32
	v_readlane_b32 s87, v242, 33
	s_waitcnt vmcnt(0)
	v_pk_fma_f32 v[134:135], v[126:127], v[138:139], v[130:131]
	v_pk_fma_f32 v[132:133], v[124:125], v[136:137], v[128:129]
	v_pk_fma_f32 v[130:131], v[122:123], v[142:143], v[148:149]
	v_pk_fma_f32 v[128:129], v[120:121], v[140:141], v[146:147]
	global_store_dwordx4 v[180:181], v[132:135], off
	global_store_dwordx4 v[180:181], v[128:131], off offset:16
	global_load_dwordx4 v[120:123], v[178:179], off nt
	global_load_dwordx4 v[124:127], v[178:179], off offset:16 nt
	v_lshlrev_b64 v[146:147], 10, v[194:195]
	v_lshl_add_u64 v[146:147], v[146:147], 0, v[202:203]
	v_lshlrev_b64 v[146:147], 2, v[146:147]
	v_lshl_add_u64 v[182:183], s[72:73], 0, v[146:147]
	v_lshlrev_b64 v[148:149], 10, v[190:191]
	v_lshl_add_u64 v[148:149], v[148:149], 0, v[202:203]
	v_lshlrev_b64 v[148:149], 2, v[148:149]
	v_lshl_add_u64 v[192:193], s[26:27], 0, v[146:147]
	v_lshl_add_u64 v[188:189], s[72:73], 0, v[148:149]
	v_lshlrev_b64 v[146:147], 10, v[186:187]
	v_lshl_add_u64 v[146:147], v[146:147], 0, v[202:203]
	v_lshlrev_b64 v[146:147], 2, v[146:147]
	v_lshl_add_u64 v[206:207], s[26:27], 0, v[148:149]
	v_lshl_add_u64 v[196:197], s[72:73], 0, v[146:147]
	v_lshlrev_b64 v[148:149], 10, v[174:175]
	v_lshl_add_u64 v[148:149], v[148:149], 0, v[202:203]
	v_lshlrev_b64 v[148:149], 2, v[148:149]
	v_lshl_add_u64 v[210:211], s[26:27], 0, v[146:147]
	v_lshl_add_u64 v[208:209], s[72:73], 0, v[148:149]
	v_lshlrev_b64 v[146:147], 10, v[172:173]
	v_lshl_add_u64 v[146:147], v[146:147], 0, v[202:203]
	v_lshlrev_b64 v[146:147], 2, v[146:147]
	v_lshl_add_u64 v[220:221], s[26:27], 0, v[148:149]
	v_lshl_add_u64 v[222:223], s[72:73], 0, v[146:147]
	v_lshlrev_b64 v[148:149], 10, v[170:171]
	v_lshl_add_u64 v[148:149], v[148:149], 0, v[202:203]
	v_lshlrev_b64 v[148:149], 2, v[148:149]
	v_lshl_add_u64 v[224:225], s[26:27], 0, v[146:147]
	v_lshl_add_u64 v[226:227], s[72:73], 0, v[148:149]
	v_lshl_add_u64 v[200:201], s[26:27], 0, v[148:149]
	s_waitcnt vmcnt(1)
	v_pk_fma_f32 v[118:119], v[118:119], v[138:139], v[122:123]
	v_pk_fma_f32 v[116:117], v[116:117], v[136:137], v[120:121]
	s_waitcnt vmcnt(0)
	v_pk_fma_f32 v[114:115], v[114:115], v[142:143], v[126:127]
	v_pk_fma_f32 v[112:113], v[112:113], v[140:141], v[124:125]
	global_store_dwordx4 v[184:185], v[116:119], off
	global_store_dwordx4 v[184:185], v[112:115], off offset:16
	global_load_dwordx4 v[120:123], v[182:183], off nt
	global_load_dwordx4 v[124:127], v[182:183], off offset:16 nt
	s_waitcnt vmcnt(1)
	v_pk_fma_f32 v[102:103], v[102:103], v[138:139], v[122:123]
	v_pk_fma_f32 v[100:101], v[100:101], v[136:137], v[120:121]
	s_waitcnt vmcnt(0)
	v_pk_fma_f32 v[98:99], v[98:99], v[142:143], v[126:127]
	v_pk_fma_f32 v[96:97], v[96:97], v[140:141], v[124:125]
	global_store_dwordx4 v[192:193], v[100:103], off
	global_store_dwordx4 v[192:193], v[96:99], off offset:16
	global_load_dwordx4 v[120:123], v[188:189], off nt
	global_load_dwordx4 v[124:127], v[188:189], off offset:16 nt
	s_waitcnt vmcnt(1)
	v_pk_fma_f32 v[86:87], v[86:87], v[138:139], v[122:123]
	v_pk_fma_f32 v[84:85], v[84:85], v[136:137], v[120:121]
	s_waitcnt vmcnt(0)
	v_pk_fma_f32 v[82:83], v[82:83], v[142:143], v[126:127]
	v_pk_fma_f32 v[80:81], v[80:81], v[140:141], v[124:125]
	global_store_dwordx4 v[206:207], v[84:87], off
	global_store_dwordx4 v[206:207], v[80:83], off offset:16
	global_load_dwordx4 v[120:123], v[196:197], off nt
	global_load_dwordx4 v[124:127], v[196:197], off offset:16 nt
	s_waitcnt vmcnt(1)
	v_pk_fma_f32 v[70:71], v[70:71], v[138:139], v[122:123]
	v_pk_fma_f32 v[68:69], v[68:69], v[136:137], v[120:121]
	s_waitcnt vmcnt(0)
;     __device__ __forceinline__ void operator()(f32x4 (&acc)[2][2][4][2], const Unit& u, int wr, int wc, int fr, int fq) const {
;     ...
;             for (int ai = 0; ai < 2; ++ai)
; #pragma unroll
;                 for (int m = 0; m < 4; ++m) {
;                     const size_t off = (size_t)(row0 + ai * HALF + m * 16) * D + col;
;                     const f32x4 x0 = *(const f32x4*)(base + off) + g0 * acc[ai][bj][m][0], x1 = *(const f32x4*)(base + off + 4) + g1 * acc[ai][bj][m][1];
;                     *(f32x4*)(out + off) = x0; *(f32x4*)(out + off + 4) = x1;
;                     acc[ai][bj][m][0] = x0; acc[ai][bj][m][1] = x1;
;                 }
;         }
; #pragma unroll
;         for (int ai = 0; ai < 2; ++ai)
; #pragma unroll
;             for (int m = 0; m < 4; ++m) {
;                 float s = 0.f;
; #pragma unroll
;                 for (int bj = 0; bj < 2; ++bj)
; #pragma unroll
;                     for (int n = 0; n < 2; ++n) { const f32x4 v = acc[ai][bj][m][n]; s += (v[0] * v[0] + v[1] * v[1]) + (v[2] * v[2] + v[3] * v[3]); }
;                 s = rows4_sum(s);
	v_pk_fma_f32 v[66:67], v[66:67], v[142:143], v[126:127]
	v_pk_fma_f32 v[64:65], v[64:65], v[140:141], v[124:125]
	global_store_dwordx4 v[210:211], v[68:71], off
	global_store_dwordx4 v[210:211], v[64:67], off offset:16
	global_load_dwordx4 v[120:123], v[208:209], off nt
	global_load_dwordx4 v[124:127], v[208:209], off offset:16 nt
	s_waitcnt vmcnt(1)
	v_pk_fma_f32 v[38:39], v[38:39], v[138:139], v[122:123]
	v_pk_fma_f32 v[36:37], v[36:37], v[136:137], v[120:121]
	s_waitcnt vmcnt(0)
	v_pk_fma_f32 v[34:35], v[34:35], v[142:143], v[126:127]
	v_pk_fma_f32 v[32:33], v[32:33], v[140:141], v[124:125]
	global_store_dwordx4 v[220:221], v[36:39], off
	global_store_dwordx4 v[220:221], v[32:35], off offset:16
	global_load_dwordx4 v[120:123], v[222:223], off nt
	global_load_dwordx4 v[124:127], v[222:223], off offset:16 nt
	s_waitcnt vmcnt(1)
	v_pk_fma_f32 v[22:23], v[22:23], v[138:139], v[122:123]
	v_pk_fma_f32 v[20:21], v[20:21], v[136:137], v[120:121]
	s_waitcnt vmcnt(0)
	v_pk_fma_f32 v[18:19], v[18:19], v[142:143], v[126:127]
	v_pk_fma_f32 v[16:17], v[16:17], v[140:141], v[124:125]
	global_store_dwordx4 v[224:225], v[20:23], off
	global_store_dwordx4 v[224:225], v[16:19], off offset:16
	global_load_dwordx4 v[120:123], v[226:227], off nt
	global_load_dwordx4 v[124:127], v[226:227], off offset:16 nt
	s_waitcnt vmcnt(1)
	v_pk_fma_f32 v[6:7], v[6:7], v[138:139], v[122:123]
	v_pk_fma_f32 v[4:5], v[4:5], v[136:137], v[120:121]
	s_waitcnt vmcnt(0)
	v_pk_fma_f32 v[2:3], v[2:3], v[142:143], v[126:127]
	v_pk_fma_f32 v[0:1], v[0:1], v[140:141], v[124:125]
	global_store_dwordx4 v[200:201], v[4:7], off
	global_store_dwordx4 v[200:201], v[0:3], off offset:16
	global_load_dwordx4 v[120:123], v[176:177], off offset:512 nt
	global_load_dwordx4 v[148:151], v[144:145], off offset:512
	s_nop 0
	global_load_dwordx4 v[144:147], v[144:145], off offset:528
	s_nop 0
	global_load_dwordx4 v[124:127], v[176:177], off offset:528 nt
	s_waitcnt vmcnt(2)
	v_pk_fma_f32 v[138:139], v[110:111], v[150:151], v[122:123]
	v_pk_fma_f32 v[136:137], v[108:109], v[148:149], v[120:121]
	s_waitcnt vmcnt(0)
	v_pk_fma_f32 v[142:143], v[106:107], v[146:147], v[126:127]
	v_pk_fma_f32 v[140:141], v[104:105], v[144:145], v[124:125]
	global_store_dwordx4 v[180:181], v[136:139], off offset:512
	global_store_dwordx4 v[180:181], v[140:143], off offset:528
	global_load_dwordx4 v[104:107], v[178:179], off offset:512 nt
	global_load_dwordx4 v[108:111], v[178:179], off offset:528 nt
	s_waitcnt vmcnt(1)
	v_pk_fma_f32 v[122:123], v[94:95], v[150:151], v[106:107]
	v_pk_fma_f32 v[120:121], v[92:93], v[148:149], v[104:105]
	s_waitcnt vmcnt(0)
	v_pk_fma_f32 v[126:127], v[90:91], v[146:147], v[110:111]
	v_pk_fma_f32 v[124:125], v[88:89], v[144:145], v[108:109]
	global_store_dwordx4 v[184:185], v[120:123], off offset:512
	global_store_dwordx4 v[184:185], v[124:127], off offset:528
	global_load_dwordx4 v[88:91], v[182:183], off offset:512 nt
	global_load_dwordx4 v[92:95], v[182:183], off offset:528 nt
	s_waitcnt vmcnt(1)
	v_pk_fma_f32 v[106:107], v[78:79], v[150:151], v[90:91]
	v_pk_fma_f32 v[104:105], v[76:77], v[148:149], v[88:89]
	s_waitcnt vmcnt(0)
	v_pk_fma_f32 v[110:111], v[74:75], v[146:147], v[94:95]
	v_pk_fma_f32 v[108:109], v[72:73], v[144:145], v[92:93]
	global_store_dwordx4 v[192:193], v[104:107], off offset:512
	global_store_dwordx4 v[192:193], v[108:111], off offset:528
	global_load_dwordx4 v[72:75], v[188:189], off offset:512 nt
	global_load_dwordx4 v[76:79], v[188:189], off offset:528 nt
	s_waitcnt vmcnt(1)
	v_pk_fma_f32 v[90:91], v[62:63], v[150:151], v[74:75]
	v_pk_fma_f32 v[88:89], v[60:61], v[148:149], v[72:73]
	s_waitcnt vmcnt(0)
	v_pk_fma_f32 v[94:95], v[58:59], v[146:147], v[78:79]
	v_pk_fma_f32 v[92:93], v[56:57], v[144:145], v[76:77]
	global_store_dwordx4 v[206:207], v[88:91], off offset:512
	global_store_dwordx4 v[206:207], v[92:95], off offset:528
	global_load_dwordx4 v[56:59], v[196:197], off offset:512 nt
	global_load_dwordx4 v[60:63], v[196:197], off offset:528 nt
	s_waitcnt vmcnt(1)
	v_pk_fma_f32 v[74:75], v[54:55], v[150:151], v[58:59]
	v_pk_fma_f32 v[72:73], v[52:53], v[148:149], v[56:57]
	s_waitcnt vmcnt(0)
	v_pk_fma_f32 v[78:79], v[50:51], v[146:147], v[62:63]
	v_pk_fma_f32 v[76:77], v[48:49], v[144:145], v[60:61]
	global_store_dwordx4 v[210:211], v[72:75], off offset:512
	global_store_dwordx4 v[210:211], v[76:79], off offset:528
	global_load_dwordx4 v[48:51], v[208:209], off offset:512 nt
	global_load_dwordx4 v[52:55], v[208:209], off offset:528 nt
	v_mul_f32_e32 v60, v143, v143
	v_fmac_f32_e32 v60, v142, v142
	v_lshlrev_b64 v[210:211], 6, v[204:205]
	s_waitcnt vmcnt(1)
	v_pk_fma_f32 v[50:51], v[46:47], v[150:151], v[50:51]
	v_pk_fma_f32 v[48:49], v[44:45], v[148:149], v[48:49]
	s_waitcnt vmcnt(0)
	v_pk_fma_f32 v[54:55], v[42:43], v[146:147], v[54:55]
	v_pk_fma_f32 v[52:53], v[40:41], v[144:145], v[52:53]
	global_store_dwordx4 v[220:221], v[48:51], off offset:512
	global_store_dwordx4 v[220:221], v[52:55], off offset:528
	global_load_dwordx4 v[40:43], v[222:223], off offset:512 nt
	global_load_dwordx4 v[44:47], v[222:223], off offset:528 nt
	s_waitcnt vmcnt(1)
	v_pk_fma_f32 v[26:27], v[26:27], v[150:151], v[42:43]
	v_pk_fma_f32 v[24:25], v[24:25], v[148:149], v[40:41]
	s_waitcnt vmcnt(0)
	v_pk_fma_f32 v[30:31], v[30:31], v[146:147], v[46:47]
	v_pk_fma_f32 v[28:29], v[28:29], v[144:145], v[44:45]
	global_store_dwordx4 v[224:225], v[24:27], off offset:512
	global_store_dwordx4 v[224:225], v[28:31], off offset:528
	global_load_dwordx4 v[42:45], v[226:227], off offset:512 nt
	global_load_dwordx4 v[56:59], v[226:227], off offset:528 nt
	v_mul_f32_e32 v40, v133, v133
	v_mul_f32_e32 v41, v135, v135
	v_mul_f32_e32 v46, v129, v129
	v_mul_f32_e32 v47, v131, v131
	v_fmac_f32_e32 v40, v132, v132
	v_fmac_f32_e32 v41, v134, v134
	v_fmac_f32_e32 v46, v128, v128
	v_fmac_f32_e32 v47, v130, v130
	v_add_f32_e32 v40, v40, v41
	v_add_f32_e32 v41, v46, v47
	v_add_f32_e32 v40, v40, v41
	v_mul_f32_e32 v41, v137, v137
	v_mul_f32_e32 v46, v139, v139
	v_mul_f32_e32 v47, v141, v141
	v_fmac_f32_e32 v41, v136, v136
	v_fmac_f32_e32 v46, v138, v138
	v_fmac_f32_e32 v47, v140, v140
	v_add_f32_e32 v41, v41, v46
	v_add_f32_e32 v46, v47, v60
	v_add_f32_e32 v40, v40, v41
	v_add_f32_e32 v40, v40, v46
	v_mov_b32_e32 v41, v40
	s_nop 1
	v_permlane32_swap_b32_e32 v40, v41
	v_add_f32_e32 v40, v40, v41
	v_mov_b32_e32 v41, v40
	s_nop 1
	v_permlane16_swap_b32_e32 v40, v41
	s_waitcnt vmcnt(1)
	v_pk_fma_f32 v[14:15], v[14:15], v[150:151], v[44:45]
	v_pk_fma_f32 v[12:13], v[12:13], v[148:149], v[42:43]
	s_waitcnt vmcnt(0)
	v_pk_fma_f32 v[10:11], v[10:11], v[146:147], v[58:59]
	v_pk_fma_f32 v[8:9], v[8:9], v[144:145], v[56:57]
	global_store_dwordx4 v[200:201], v[12:15], off offset:512
	global_store_dwordx4 v[200:201], v[8:11], off offset:528
	s_and_saveexec_b64 s[24:25], s[40:41]
	s_cbranch_execz .LBB0_742
;     __device__ __forceinline__ void operator()(f32x4 (&acc)[2][2][4][2], const Unit& u, int wr, int wc, int fr, int fq) const {
;     ...
;                 s = rows4_sum(s);
;                 if (fq == 0) __hip_atomic_store(slots + (size_t)(row0 + ai * HALF + m * 16) * 16 + u.pn * 4 + wc, s, __ATOMIC_RELAXED, __HIP_MEMORY_SCOPE_AGENT);
	v_add_f32_e32 v42, v40, v41
	v_lshl_add_u64 v[40:41], s[8:9], 0, v[210:211]
	v_lshl_add_u64 v[40:41], s[22:23], 2, v[40:41]
	s_lshl_b32 s0, s58, 2
	v_lshl_add_u64 v[40:41], v[40:41], 0, s[0:1]
	global_store_dword v[40:41], v42, off sc1

;     __device__ __forceinline__ void operator()(const f32x4 (&acc)[2][2][4][2], const Unit& u, int wr, int wc, int fr, int fq) const {
;     ...
;         for (int bj = 0; bj < 2; ++bj)
; #pragma unroll
;             for (int n = 0; n < 2; ++n) {
;                 const int col = col0 + bj * HALF + n * 16;
;                 const f32x4 g = *(const f32x4*)(gp + col);
; #pragma unroll
;                 for (int ai = 0; ai < 2; ++ai)
; #pragma unroll
;                     for (int m = 0; m < 4; ++m) {
;                         const size_t off = (size_t)(row0 + ai * HALF + m * 16) * D + col;
;                         *(f32x4*)(out + off) = *(const f32x4*)(base + off) + g * acc[ai][bj][m][n];
.LBB0_914:
	v_lshl_add_u32 v210, s49, 8, v218
	v_lshl_add_u32 v212, s50, 8, v220
	v_mov_b32_e32 v211, 0
	v_mov_b32_e32 v213, 0
	v_lshlrev_b64 v[210:211], 12, v[210:211]
	v_lshlrev_b32_e32 v212, 2, v212
	s_lshr_b32 s18, s49, 4
	s_mul_i32 s18, s18, 0x6000
	s_add_u32 s18, s28, s18
	s_addc_u32 s19, s29, 0
	v_lshl_add_u64 v[192:193], s[26:27], 0, v[210:211]
	v_lshl_add_u64 v[208:209], s[18:19], 0, v[212:213]
	v_lshl_add_u64 v[192:193], v[192:193], 0, v[212:213]
	global_load_dwordx4 v[224:227], v[208:209], off
	global_load_dwordx4 v[228:231], v[208:209], off offset:64
	global_load_dwordx4 v[232:235], v[208:209], off offset:512
	global_load_dwordx4 v[236:239], v[208:209], off offset:576
	global_load_dwordx4 v[128:131], v[192:193], off nt
	global_load_dwordx4 v[132:135], v[192:193], off offset:64 nt
	global_load_dwordx4 v[136:139], v[192:193], off offset:512 nt
	global_load_dwordx4 v[140:143], v[192:193], off offset:576 nt
	s_mov_b64 s[18:19], 0x10000
	v_lshl_add_u64 v[194:195], v[192:193], 0, s[18:19]
	global_load_dwordx4 v[144:147], v[194:195], off nt
	global_load_dwordx4 v[148:151], v[194:195], off offset:64 nt
	global_load_dwordx4 v[152:155], v[194:195], off offset:512 nt
	global_load_dwordx4 v[156:159], v[194:195], off offset:576 nt
	s_mov_b64 s[18:19], 0x20000
	v_lshl_add_u64 v[196:197], v[192:193], 0, s[18:19]
	global_load_dwordx4 v[160:163], v[196:197], off nt
	global_load_dwordx4 v[164:167], v[196:197], off offset:64 nt
	global_load_dwordx4 v[168:171], v[196:197], off offset:512 nt
	global_load_dwordx4 v[172:175], v[196:197], off offset:576 nt
	s_mov_b64 s[18:19], 0x30000
	v_lshl_add_u64 v[198:199], v[192:193], 0, s[18:19]
	v_lshl_add_u64 v[200:201], v[192:193], 0, s[10:11]
	v_lshl_add_u64 v[202:203], v[192:193], 0, s[12:13]
	v_lshl_add_u64 v[204:205], v[192:193], 0, s[14:15]
	v_lshl_add_u64 v[206:207], v[192:193], 0, s[6:7]
	s_waitcnt vmcnt(8)
	v_pk_fma_f32 v[124:125], v[124:125], v[224:225], v[128:129]
	v_pk_fma_f32 v[126:127], v[126:127], v[226:227], v[130:131]
	v_pk_fma_f32 v[108:109], v[108:109], v[228:229], v[132:133]
	v_pk_fma_f32 v[110:111], v[110:111], v[230:231], v[134:135]
	v_pk_fma_f32 v[80:81], v[80:81], v[232:233], v[136:137]
	v_pk_fma_f32 v[82:83], v[82:83], v[234:235], v[138:139]
	v_pk_fma_f32 v[48:49], v[48:49], v[236:237], v[140:141]
	v_pk_fma_f32 v[50:51], v[50:51], v[238:239], v[142:143]
	global_store_dwordx4 v[192:193], v[124:127], off
	global_store_dwordx4 v[192:193], v[108:111], off offset:64
	global_store_dwordx4 v[192:193], v[80:83], off offset:512
	global_store_dwordx4 v[192:193], v[48:51], off offset:576
	global_load_dwordx4 v[128:131], v[198:199], off nt
	global_load_dwordx4 v[132:135], v[198:199], off offset:64 nt
	global_load_dwordx4 v[136:139], v[198:199], off offset:512 nt
	global_load_dwordx4 v[140:143], v[198:199], off offset:576 nt
	s_waitcnt vmcnt(12)
	v_pk_fma_f32 v[120:121], v[120:121], v[224:225], v[144:145]
	v_pk_fma_f32 v[122:123], v[122:123], v[226:227], v[146:147]
	v_pk_fma_f32 v[104:105], v[104:105], v[228:229], v[148:149]
	v_pk_fma_f32 v[106:107], v[106:107], v[230:231], v[150:151]
	v_pk_fma_f32 v[76:77], v[76:77], v[232:233], v[152:153]
	v_pk_fma_f32 v[78:79], v[78:79], v[234:235], v[154:155]
	v_pk_fma_f32 v[40:41], v[40:41], v[236:237], v[156:157]
	v_pk_fma_f32 v[42:43], v[42:43], v[238:239], v[158:159]
	global_store_dwordx4 v[194:195], v[120:123], off
	global_store_dwordx4 v[194:195], v[104:107], off offset:64
	global_store_dwordx4 v[194:195], v[76:79], off offset:512
	global_store_dwordx4 v[194:195], v[40:43], off offset:576
	global_load_dwordx4 v[144:147], v[200:201], off nt
	global_load_dwordx4 v[148:151], v[200:201], off offset:64 nt
	global_load_dwordx4 v[152:155], v[200:201], off offset:512 nt
	global_load_dwordx4 v[156:159], v[200:201], off offset:576 nt
	s_waitcnt vmcnt(16)
	v_pk_fma_f32 v[116:117], v[116:117], v[224:225], v[160:161]
	v_pk_fma_f32 v[118:119], v[118:119], v[226:227], v[162:163]
	v_pk_fma_f32 v[100:101], v[100:101], v[228:229], v[164:165]
	v_pk_fma_f32 v[102:103], v[102:103], v[230:231], v[166:167]
	v_pk_fma_f32 v[64:65], v[64:65], v[232:233], v[168:169]
	v_pk_fma_f32 v[66:67], v[66:67], v[234:235], v[170:171]
	v_pk_fma_f32 v[36:37], v[36:37], v[236:237], v[172:173]
	v_pk_fma_f32 v[38:39], v[38:39], v[238:239], v[174:175]
	global_store_dwordx4 v[196:197], v[116:119], off
	global_store_dwordx4 v[196:197], v[100:103], off offset:64
	global_store_dwordx4 v[196:197], v[64:67], off offset:512
	global_store_dwordx4 v[196:197], v[36:39], off offset:576
	global_load_dwordx4 v[160:163], v[202:203], off nt
	global_load_dwordx4 v[164:167], v[202:203], off offset:64 nt
	global_load_dwordx4 v[168:171], v[202:203], off offset:512 nt
	global_load_dwordx4 v[172:175], v[202:203], off offset:576 nt
	s_waitcnt vmcnt(16)
;     __device__ __forceinline__ void operator()(const f32x4 (&acc)[2][2][4][2], const Unit& u, int wr, int wc, int fr, int fq) const {
;     ...
;             for (int n = 0; n < 2; ++n) {
;                 const int col = col0 + bj * HALF + n * 16;
;                 const f32x4 g = *(const f32x4*)(gp + col);
; #pragma unroll
;                 for (int ai = 0; ai < 2; ++ai)
; #pragma unroll
;                     for (int m = 0; m < 4; ++m) {
;                         const size_t off = (size_t)(row0 + ai * HALF + m * 16) * D + col;
;                         *(f32x4*)(out + off) = *(const f32x4*)(base + off) + g * acc[ai][bj][m][n];
;                     }
	v_pk_fma_f32 v[112:113], v[112:113], v[224:225], v[128:129]
	v_pk_fma_f32 v[114:115], v[114:115], v[226:227], v[130:131]
	v_pk_fma_f32 v[96:97], v[96:97], v[228:229], v[132:133]
	v_pk_fma_f32 v[98:99], v[98:99], v[230:231], v[134:135]
	v_pk_fma_f32 v[56:57], v[56:57], v[232:233], v[136:137]
	v_pk_fma_f32 v[58:59], v[58:59], v[234:235], v[138:139]
	v_pk_fma_f32 v[32:33], v[32:33], v[236:237], v[140:141]
	v_pk_fma_f32 v[34:35], v[34:35], v[238:239], v[142:143]
	global_store_dwordx4 v[198:199], v[112:115], off
	global_store_dwordx4 v[198:199], v[96:99], off offset:64
	global_store_dwordx4 v[198:199], v[56:59], off offset:512
	global_store_dwordx4 v[198:199], v[32:35], off offset:576
	global_load_dwordx4 v[128:131], v[204:205], off nt
	global_load_dwordx4 v[132:135], v[204:205], off offset:64 nt
	global_load_dwordx4 v[136:139], v[204:205], off offset:512 nt
	global_load_dwordx4 v[140:143], v[204:205], off offset:576 nt
	s_waitcnt vmcnt(16)
	v_pk_fma_f32 v[92:93], v[92:93], v[224:225], v[144:145]
	v_pk_fma_f32 v[94:95], v[94:95], v[226:227], v[146:147]
	v_pk_fma_f32 v[68:69], v[68:69], v[228:229], v[148:149]
	v_pk_fma_f32 v[70:71], v[70:71], v[230:231], v[150:151]
	v_pk_fma_f32 v[28:29], v[28:29], v[232:233], v[152:153]
	v_pk_fma_f32 v[30:31], v[30:31], v[234:235], v[154:155]
	v_pk_fma_f32 v[12:13], v[12:13], v[236:237], v[156:157]
	v_pk_fma_f32 v[14:15], v[14:15], v[238:239], v[158:159]
	global_store_dwordx4 v[200:201], v[92:95], off
	global_store_dwordx4 v[200:201], v[68:71], off offset:64
	global_store_dwordx4 v[200:201], v[28:31], off offset:512
	global_store_dwordx4 v[200:201], v[12:15], off offset:576
	global_load_dwordx4 v[144:147], v[206:207], off nt
	global_load_dwordx4 v[148:151], v[206:207], off offset:64 nt
	global_load_dwordx4 v[152:155], v[206:207], off offset:512 nt
	global_load_dwordx4 v[156:159], v[206:207], off offset:576 nt
	s_waitcnt vmcnt(16)
	v_pk_fma_f32 v[88:89], v[88:89], v[224:225], v[160:161]
	v_pk_fma_f32 v[90:91], v[90:91], v[226:227], v[162:163]
	v_pk_fma_f32 v[60:61], v[60:61], v[228:229], v[164:165]
	v_pk_fma_f32 v[62:63], v[62:63], v[230:231], v[166:167]
	v_pk_fma_f32 v[24:25], v[24:25], v[232:233], v[168:169]
	v_pk_fma_f32 v[26:27], v[26:27], v[234:235], v[170:171]
	v_pk_fma_f32 v[8:9], v[8:9], v[236:237], v[172:173]
	v_pk_fma_f32 v[10:11], v[10:11], v[238:239], v[174:175]
	global_store_dwordx4 v[202:203], v[88:91], off
	global_store_dwordx4 v[202:203], v[60:63], off offset:64
	global_store_dwordx4 v[202:203], v[24:27], off offset:512
	global_store_dwordx4 v[202:203], v[8:11], off offset:576
	s_waitcnt vmcnt(12)
	v_pk_fma_f32 v[84:85], v[84:85], v[224:225], v[128:129]
	v_pk_fma_f32 v[86:87], v[86:87], v[226:227], v[130:131]
	v_pk_fma_f32 v[52:53], v[52:53], v[228:229], v[132:133]
	v_pk_fma_f32 v[54:55], v[54:55], v[230:231], v[134:135]
	v_pk_fma_f32 v[20:21], v[20:21], v[232:233], v[136:137]
	v_pk_fma_f32 v[22:23], v[22:23], v[234:235], v[138:139]
	v_pk_fma_f32 v[4:5], v[4:5], v[236:237], v[140:141]
	v_pk_fma_f32 v[6:7], v[6:7], v[238:239], v[142:143]
	global_store_dwordx4 v[204:205], v[84:87], off
	global_store_dwordx4 v[204:205], v[52:55], off offset:64
	global_store_dwordx4 v[204:205], v[20:23], off offset:512
	global_store_dwordx4 v[204:205], v[4:7], off offset:576
	s_waitcnt vmcnt(8)
	v_pk_fma_f32 v[72:73], v[72:73], v[224:225], v[144:145]
	v_pk_fma_f32 v[74:75], v[74:75], v[226:227], v[146:147]
	v_pk_fma_f32 v[44:45], v[44:45], v[228:229], v[148:149]
	v_pk_fma_f32 v[46:47], v[46:47], v[230:231], v[150:151]
	v_pk_fma_f32 v[16:17], v[16:17], v[232:233], v[152:153]
	v_pk_fma_f32 v[18:19], v[18:19], v[234:235], v[154:155]
	v_pk_fma_f32 v[0:1], v[0:1], v[236:237], v[156:157]
	v_pk_fma_f32 v[2:3], v[2:3], v[238:239], v[158:159]
	global_store_dwordx4 v[206:207], v[72:75], off
	global_store_dwordx4 v[206:207], v[44:47], off offset:64
	global_store_dwordx4 v[206:207], v[16:19], off offset:512
	global_store_dwordx4 v[206:207], v[0:3], off offset:576
	s_and_b64 vcc, exec, s[0:1]
	s_mov_b64 s[0:1], -1
	s_cbranch_vccnz .LBB0_899
	s_and_b64 vcc, exec, s[62:63]
	s_cbranch_vccnz .LBB0_898
	s_barrier
	s_branch .LBB0_898
